# FFN-up SwiGLU epilogue: the four per-row-scale table ds_read2 issued together at the top (fresh registers) instead of four read+wait round trips
# baseline (speedup 1.0000x reference)
; DI unsigned pack2(float lo, float hi) { f32x2_t v = {lo, hi}; return __builtin_bit_cast(unsigned, __builtin_convertvector(v, bf16x2_t)); }
; #define PG8_LAS __attribute__((address_space(3)))
;   DI void operator()(const f32x4 (&acc)[2][2][4][2], const Unit& u, int wr, int wc, int fr, int fq, const PG8_LAS float* rt) const {
;     const int row0 = u.pm * BM + wr * 64 + fr, col0 = u.pn * HALF + wc * 32 + 8 * fq;
; #pragma unroll
;     for (int ai = 0; ai < 2; ++ai)
; #pragma unroll
;       for (int m = 0; m < 4; ++m) {
;         const float r = rt[ai * HALF + wr * 64 + m * 16 + fr];
;         float a[8];
; #pragma unroll
;         for (int n = 0; n < 2; ++n)
; #pragma unroll
;           for (int j = 0; j < 4; ++j) { const float u1 = acc[ai][0][m][n][j] * r, u3 = acc[ai][1][m][n][j] * r; a[4 * n + j] = u1 * u3 * __builtin_amdgcn_rcpf(1.f + __builtin_amdgcn_exp2f(-LOG2E * u1)); }
;         u32x4 w; w.x = pack2(a[0], a[1]); w.y = pack2(a[2], a[3]); w.z = pack2(a[4], a[5]); w.w = pack2(a[6], a[7]);
;         *(u32x4*)(O + (size_t)(row0 + ai * HALF + m * 16) * DFF + col0) = w; }
;   }
.LBB0_608:
	s_lshl_b32 s8, s8, 10
	s_and_b32 s8, s8, 0x400
	v_add_u32_e32 v159, s8, v156
	ds_read2_b32 v[148:149], v159 offset1:16
	ds_read2_b32 v[166:167], v159 offset0:32 offset1:48
	ds_read2_b32 v[168:169], v159 offset0:128 offset1:144
	ds_read2_b32 v[170:171], v159 offset0:160 offset1:176
	v_lshl_or_b32 v146, s9, 7, v157
	v_lshl_add_u32 v158, s19, 8, v153
	v_ashrrev_i32_e32 v147, 31, v146
	s_mov_b64 s[28:29], -1
	s_waitcnt lgkmcnt(0)
	v_pk_mul_f32 v[130:131], v[130:131], v[148:149] op_sel_hi:[1,0]
	v_pk_mul_f32 v[126:127], v[126:127], v[148:149] op_sel_hi:[1,0]
	v_mul_f32_e32 v160, 0xbfb8aa3b, v130
	v_pk_mul_f32 v[126:127], v[130:131], v[126:127]
	v_mul_f32_e32 v130, 0xbfb8aa3b, v131
	v_exp_f32_e32 v130, v130
	v_pk_mul_f32 v[128:129], v[128:129], v[148:149] op_sel_hi:[1,0]
	v_pk_mul_f32 v[122:123], v[122:123], v[148:149] op_sel_hi:[1,0]
	v_pk_mul_f32 v[118:119], v[118:119], v[148:149] op_sel_hi:[1,0]
	v_add_f32_e32 v130, 1.0, v130
	v_rcp_f32_e32 v161, v130
	v_pk_mul_f32 v[130:131], v[132:133], v[148:149] op_sel_hi:[1,0]
	v_pk_mul_f32 v[118:119], v[122:123], v[118:119]
	v_mul_f32_e32 v132, 0xbfb8aa3b, v130
	v_pk_mul_f32 v[128:129], v[130:131], v[128:129]
	v_mul_f32_e32 v130, 0xbfb8aa3b, v131
	v_exp_f32_e32 v130, v130
	v_pk_mul_f32 v[120:121], v[120:121], v[148:149] op_sel_hi:[1,0]
	v_exp_f32_e32 v160, v160
	v_exp_f32_e32 v132, v132
	v_add_f32_e32 v130, 1.0, v130
	v_rcp_f32_e32 v133, v130
	v_mul_f32_e32 v130, 0xbfb8aa3b, v122
	v_mul_f32_e32 v122, 0xbfb8aa3b, v123
	v_exp_f32_e32 v122, v122
	v_exp_f32_e32 v130, v130
	v_add_f32_e32 v160, 1.0, v160
	v_rcp_f32_e32 v160, v160
	v_add_f32_e32 v122, 1.0, v122
	v_rcp_f32_e32 v131, v122
	v_pk_mul_f32 v[122:123], v[124:125], v[148:149] op_sel_hi:[1,0]
	v_add_f32_e32 v130, 1.0, v130
	v_mul_f32_e32 v124, 0xbfb8aa3b, v122
	v_pk_mul_f32 v[120:121], v[122:123], v[120:121]
	v_mul_f32_e32 v122, 0xbfb8aa3b, v123
	v_exp_f32_e32 v124, v124
	v_exp_f32_e32 v122, v122
	v_rcp_f32_e32 v130, v130
	v_add_f32_e32 v132, 1.0, v132
	v_add_f32_e32 v124, 1.0, v124
	v_add_f32_e32 v122, 1.0, v122
	v_rcp_f32_e32 v124, v124
	v_rcp_f32_e32 v125, v122
	v_rcp_f32_e32 v132, v132
	v_pk_mul_f32 v[118:119], v[118:119], v[130:131]
	v_pk_mul_f32 v[126:127], v[126:127], v[160:161]
	v_pk_mul_f32 v[120:121], v[120:121], v[124:125]
	v_cvt_pk_bf16_f32 v124, v118, v119
	v_mov_b64_e32 v[118:119], s[66:67]
	v_pk_mul_f32 v[128:129], v[128:129], v[132:133]
	v_cvt_pk_bf16_f32 v122, v126, v127
	v_cvt_pk_bf16_f32 v125, v120, v121
	v_mad_i64_i32 v[126:127], s[8:9], v158, s43, v[118:119]
	v_lshlrev_b64 v[120:121], 1, v[146:147]
	v_cvt_pk_bf16_f32 v123, v128, v129
	v_lshl_add_u64 v[126:127], v[126:127], 0, v[120:121]
	global_store_dwordx4 v[126:127], v[122:125], off
	s_andn2_b64 vcc, exec, s[38:39]
	s_nop 0
	v_mov_b32_e32 v122, v149
	v_pk_mul_f32 v[114:115], v[114:115], v[122:123] op_sel_hi:[1,0]
	s_nop 0
	v_mul_f32_e32 v123, 0xbfb8aa3b, v114
	v_exp_f32_e32 v123, v123
	s_nop 0
	v_add_f32_e32 v123, 1.0, v123
	v_pk_mul_f32 v[110:111], v[110:111], v[122:123] op_sel_hi:[1,0]
	v_pk_mul_f32 v[112:113], v[112:113], v[122:123] op_sel_hi:[1,0]
	v_pk_mul_f32 v[110:111], v[114:115], v[110:111]
	v_mul_f32_e32 v114, 0xbfb8aa3b, v115
	v_exp_f32_e32 v114, v114
	v_pk_mul_f32 v[106:107], v[106:107], v[122:123] op_sel_hi:[1,0]
	v_pk_mul_f32 v[102:103], v[102:103], v[122:123] op_sel_hi:[1,0]
	v_pk_mul_f32 v[104:105], v[104:105], v[122:123] op_sel_hi:[1,0]
	v_add_f32_e32 v114, 1.0, v114
	v_rcp_f32_e32 v125, v114
	v_pk_mul_f32 v[114:115], v[116:117], v[122:123] op_sel_hi:[1,0]
	v_pk_mul_f32 v[102:103], v[106:107], v[102:103]
	v_mul_f32_e32 v116, 0xbfb8aa3b, v114
	v_pk_mul_f32 v[112:113], v[114:115], v[112:113]
	v_mul_f32_e32 v114, 0xbfb8aa3b, v115
	v_exp_f32_e32 v114, v114
	v_exp_f32_e32 v116, v116
	v_rcp_f32_e32 v124, v123
	v_add_f32_e32 v114, 1.0, v114
	v_rcp_f32_e32 v117, v114
	v_mul_f32_e32 v114, 0xbfb8aa3b, v106
	v_mul_f32_e32 v106, 0xbfb8aa3b, v107
	v_exp_f32_e32 v114, v114
	v_exp_f32_e32 v106, v106
	v_add_f32_e32 v116, 1.0, v116
	v_rcp_f32_e32 v116, v116
	v_add_f32_e32 v114, 1.0, v114
	v_add_f32_e32 v106, 1.0, v106
	v_rcp_f32_e32 v114, v114
	v_rcp_f32_e32 v115, v106
	v_pk_mul_f32 v[110:111], v[110:111], v[124:125]
	v_pk_mul_f32 v[112:113], v[112:113], v[116:117]
	v_pk_mul_f32 v[106:107], v[102:103], v[114:115]
	v_pk_mul_f32 v[102:103], v[108:109], v[122:123] op_sel_hi:[1,0]
	s_nop 0
	v_mul_f32_e32 v108, 0xbfb8aa3b, v102
	v_pk_mul_f32 v[104:105], v[102:103], v[104:105]
	v_mul_f32_e32 v102, 0xbfb8aa3b, v103
	v_exp_f32_e32 v108, v108
	v_exp_f32_e32 v102, v102
	v_cvt_pk_bf16_f32 v103, v112, v113
	v_add_f32_e32 v108, 1.0, v108
	v_add_f32_e32 v102, 1.0, v102
	v_rcp_f32_e32 v108, v108
	v_rcp_f32_e32 v109, v102
	v_cvt_pk_bf16_f32 v102, v110, v111
	v_pk_mul_f32 v[108:109], v[104:105], v[108:109]
	v_cvt_pk_bf16_f32 v104, v106, v107
	v_or_b32_e32 v106, 16, v158
	v_mad_i64_i32 v[106:107], s[8:9], v106, s43, v[118:119]
	v_cvt_pk_bf16_f32 v105, v108, v109
	v_lshl_add_u64 v[106:107], v[106:107], 0, v[120:121]
	global_store_dwordx4 v[106:107], v[102:105], off
	s_waitcnt lgkmcnt(0)
; DI unsigned pack2(float lo, float hi) { f32x2_t v = {lo, hi}; return __builtin_bit_cast(unsigned, __builtin_convertvector(v, bf16x2_t)); }
; #define PG8_LAS __attribute__((address_space(3)))
;   DI void operator()(const f32x4 (&acc)[2][2][4][2], const Unit& u, int wr, int wc, int fr, int fq, const PG8_LAS float* rt) const {
;     const int row0 = u.pm * BM + wr * 64 + fr, col0 = u.pn * HALF + wc * 32 + 8 * fq;
; #pragma unroll
;     for (int ai = 0; ai < 2; ++ai)
; #pragma unroll
;       for (int m = 0; m < 4; ++m) {
;         const float r = rt[ai * HALF + wr * 64 + m * 16 + fr];
;         float a[8];
; #pragma unroll
;         for (int n = 0; n < 2; ++n)
; #pragma unroll
;           for (int j = 0; j < 4; ++j) { const float u1 = acc[ai][0][m][n][j] * r, u3 = acc[ai][1][m][n][j] * r; a[4 * n + j] = u1 * u3 * __builtin_amdgcn_rcpf(1.f + __builtin_amdgcn_exp2f(-LOG2E * u1)); }
;         u32x4 w; w.x = pack2(a[0], a[1]); w.y = pack2(a[2], a[3]); w.z = pack2(a[4], a[5]); w.w = pack2(a[6], a[7]);
;         *(u32x4*)(O + (size_t)(row0 + ai * HALF + m * 16) * DFF + col0) = w; }
;   }
	v_pk_mul_f32 v[98:99], v[98:99], v[166:167] op_sel_hi:[1,0]
	v_pk_mul_f32 v[94:95], v[94:95], v[166:167] op_sel_hi:[1,0]
	v_mul_f32_e32 v104, 0xbfb8aa3b, v98
	v_pk_mul_f32 v[94:95], v[98:99], v[94:95]
	v_mul_f32_e32 v98, 0xbfb8aa3b, v99
	v_exp_f32_e32 v98, v98
	v_pk_mul_f32 v[96:97], v[96:97], v[166:167] op_sel_hi:[1,0]
	v_pk_mul_f32 v[90:91], v[90:91], v[166:167] op_sel_hi:[1,0]
	v_pk_mul_f32 v[86:87], v[86:87], v[166:167] op_sel_hi:[1,0]
	v_add_f32_e32 v98, 1.0, v98
	v_rcp_f32_e32 v105, v98
	v_pk_mul_f32 v[98:99], v[100:101], v[166:167] op_sel_hi:[1,0]
	v_pk_mul_f32 v[86:87], v[90:91], v[86:87]
	v_mul_f32_e32 v100, 0xbfb8aa3b, v98
	v_pk_mul_f32 v[96:97], v[98:99], v[96:97]
	v_mul_f32_e32 v98, 0xbfb8aa3b, v99
	v_exp_f32_e32 v98, v98
	v_pk_mul_f32 v[88:89], v[88:89], v[166:167] op_sel_hi:[1,0]
	v_exp_f32_e32 v104, v104
	v_exp_f32_e32 v100, v100
	v_add_f32_e32 v98, 1.0, v98
	v_rcp_f32_e32 v101, v98
	v_mul_f32_e32 v98, 0xbfb8aa3b, v90
	v_mul_f32_e32 v90, 0xbfb8aa3b, v91
	v_exp_f32_e32 v98, v98
	v_exp_f32_e32 v90, v90
	v_add_f32_e32 v104, 1.0, v104
	v_add_f32_e32 v100, 1.0, v100
	v_add_f32_e32 v98, 1.0, v98
	v_add_f32_e32 v90, 1.0, v90
	v_rcp_f32_e32 v98, v98
	v_rcp_f32_e32 v99, v90
	v_rcp_f32_e32 v104, v104
	v_rcp_f32_e32 v100, v100
	v_pk_mul_f32 v[90:91], v[86:87], v[98:99]
	v_pk_mul_f32 v[86:87], v[92:93], v[166:167] op_sel_hi:[1,0]
	v_pk_mul_f32 v[94:95], v[94:95], v[104:105]
	v_mul_f32_e32 v92, 0xbfb8aa3b, v86
	v_pk_mul_f32 v[88:89], v[86:87], v[88:89]
	v_mul_f32_e32 v86, 0xbfb8aa3b, v87
	v_exp_f32_e32 v92, v92
	v_exp_f32_e32 v86, v86
	v_pk_mul_f32 v[96:97], v[96:97], v[100:101]
	v_add_f32_e32 v92, 1.0, v92
	v_add_f32_e32 v86, 1.0, v86
	v_rcp_f32_e32 v92, v92
	v_rcp_f32_e32 v93, v86
	v_cvt_pk_bf16_f32 v86, v94, v95
	v_cvt_pk_bf16_f32 v87, v96, v97
	v_pk_mul_f32 v[92:93], v[88:89], v[92:93]
	v_cvt_pk_bf16_f32 v88, v90, v91
	v_or_b32_e32 v90, 32, v158
	v_mad_i64_i32 v[90:91], s[8:9], v90, s43, v[118:119]
	v_cvt_pk_bf16_f32 v89, v92, v93
	v_lshl_add_u64 v[90:91], v[90:91], 0, v[120:121]
	global_store_dwordx4 v[90:91], v[86:89], off
	s_nop 1
	v_mov_b32_e32 v86, v167
	v_pk_mul_f32 v[82:83], v[82:83], v[86:87] op_sel_hi:[1,0]
	s_nop 0
	v_mul_f32_e32 v87, 0xbfb8aa3b, v82
	v_exp_f32_e32 v87, v87
	s_nop 0
	v_add_f32_e32 v87, 1.0, v87
	v_pk_mul_f32 v[78:79], v[78:79], v[86:87] op_sel_hi:[1,0]
	v_pk_mul_f32 v[80:81], v[80:81], v[86:87] op_sel_hi:[1,0]
	v_pk_mul_f32 v[78:79], v[82:83], v[78:79]
	v_mul_f32_e32 v82, 0xbfb8aa3b, v83
	v_exp_f32_e32 v82, v82
	v_pk_mul_f32 v[74:75], v[74:75], v[86:87] op_sel_hi:[1,0]
	v_pk_mul_f32 v[70:71], v[70:71], v[86:87] op_sel_hi:[1,0]
	v_pk_mul_f32 v[72:73], v[72:73], v[86:87] op_sel_hi:[1,0]
	v_add_f32_e32 v82, 1.0, v82
	v_rcp_f32_e32 v89, v82
	v_pk_mul_f32 v[82:83], v[84:85], v[86:87] op_sel_hi:[1,0]
	v_pk_mul_f32 v[70:71], v[74:75], v[70:71]
	v_mul_f32_e32 v84, 0xbfb8aa3b, v82
	v_pk_mul_f32 v[80:81], v[82:83], v[80:81]
	v_mul_f32_e32 v82, 0xbfb8aa3b, v83
	v_exp_f32_e32 v82, v82
	v_exp_f32_e32 v84, v84
	v_rcp_f32_e32 v88, v87
	v_add_f32_e32 v82, 1.0, v82
	v_rcp_f32_e32 v85, v82
	v_mul_f32_e32 v82, 0xbfb8aa3b, v74
	v_mul_f32_e32 v74, 0xbfb8aa3b, v75
	v_exp_f32_e32 v82, v82
	v_exp_f32_e32 v74, v74
	v_add_f32_e32 v84, 1.0, v84
	v_rcp_f32_e32 v84, v84
	v_add_f32_e32 v82, 1.0, v82
	v_add_f32_e32 v74, 1.0, v74
	v_rcp_f32_e32 v82, v82
	v_rcp_f32_e32 v83, v74
	v_pk_mul_f32 v[78:79], v[78:79], v[88:89]
	v_pk_mul_f32 v[80:81], v[80:81], v[84:85]
	v_pk_mul_f32 v[74:75], v[70:71], v[82:83]
	v_pk_mul_f32 v[70:71], v[76:77], v[86:87] op_sel_hi:[1,0]
	s_nop 0
	v_mul_f32_e32 v76, 0xbfb8aa3b, v70
	v_pk_mul_f32 v[72:73], v[70:71], v[72:73]
	v_mul_f32_e32 v70, 0xbfb8aa3b, v71
	v_exp_f32_e32 v76, v76
	v_exp_f32_e32 v70, v70
	v_cvt_pk_bf16_f32 v71, v80, v81
	v_add_f32_e32 v76, 1.0, v76
	v_add_f32_e32 v70, 1.0, v70
	v_rcp_f32_e32 v76, v76
	v_rcp_f32_e32 v77, v70
	v_cvt_pk_bf16_f32 v70, v78, v79
	v_pk_mul_f32 v[76:77], v[72:73], v[76:77]
	v_cvt_pk_bf16_f32 v72, v74, v75
	v_or_b32_e32 v74, 48, v158
	v_mad_i64_i32 v[74:75], s[8:9], v74, s43, v[118:119]
	v_cvt_pk_bf16_f32 v73, v76, v77
	v_lshl_add_u64 v[74:75], v[74:75], 0, v[120:121]
	global_store_dwordx4 v[74:75], v[70:73], off
	v_add_u32_e32 v74, 0x80, v158
	s_waitcnt lgkmcnt(0)
	v_pk_mul_f32 v[66:67], v[66:67], v[168:169] op_sel_hi:[1,0]
	v_pk_mul_f32 v[62:63], v[62:63], v[168:169] op_sel_hi:[1,0]
	v_mul_f32_e32 v72, 0xbfb8aa3b, v66
	v_pk_mul_f32 v[62:63], v[66:67], v[62:63]
	v_mul_f32_e32 v66, 0xbfb8aa3b, v67
	v_exp_f32_e32 v66, v66
	v_pk_mul_f32 v[64:65], v[64:65], v[168:169] op_sel_hi:[1,0]
	v_pk_mul_f32 v[58:59], v[58:59], v[168:169] op_sel_hi:[1,0]
	v_pk_mul_f32 v[54:55], v[54:55], v[168:169] op_sel_hi:[1,0]
	v_add_f32_e32 v66, 1.0, v66
	v_rcp_f32_e32 v73, v66
	v_pk_mul_f32 v[66:67], v[68:69], v[168:169] op_sel_hi:[1,0]
	v_pk_mul_f32 v[54:55], v[58:59], v[54:55]
	v_mul_f32_e32 v68, 0xbfb8aa3b, v66
	v_pk_mul_f32 v[64:65], v[66:67], v[64:65]
	v_mul_f32_e32 v66, 0xbfb8aa3b, v67
	v_exp_f32_e32 v66, v66
	v_pk_mul_f32 v[56:57], v[56:57], v[168:169] op_sel_hi:[1,0]
	v_exp_f32_e32 v72, v72
	v_exp_f32_e32 v68, v68
	v_add_f32_e32 v66, 1.0, v66
	v_rcp_f32_e32 v69, v66
	v_mul_f32_e32 v66, 0xbfb8aa3b, v58
	v_mul_f32_e32 v58, 0xbfb8aa3b, v59
	v_exp_f32_e32 v66, v66
	v_exp_f32_e32 v58, v58
	v_add_f32_e32 v72, 1.0, v72
	v_add_f32_e32 v68, 1.0, v68
	v_add_f32_e32 v66, 1.0, v66
	v_add_f32_e32 v58, 1.0, v58
	v_rcp_f32_e32 v66, v66
	v_rcp_f32_e32 v67, v58
	v_rcp_f32_e32 v72, v72
	v_rcp_f32_e32 v68, v68
	v_pk_mul_f32 v[58:59], v[54:55], v[66:67]
	v_pk_mul_f32 v[54:55], v[60:61], v[168:169] op_sel_hi:[1,0]
	v_pk_mul_f32 v[62:63], v[62:63], v[72:73]
	v_mul_f32_e32 v60, 0xbfb8aa3b, v54
; DI unsigned pack2(float lo, float hi) { f32x2_t v = {lo, hi}; return __builtin_bit_cast(unsigned, __builtin_convertvector(v, bf16x2_t)); }
; #define PG8_LAS __attribute__((address_space(3)))
;   DI void operator()(const f32x4 (&acc)[2][2][4][2], const Unit& u, int wr, int wc, int fr, int fq, const PG8_LAS float* rt) const {
;     const int row0 = u.pm * BM + wr * 64 + fr, col0 = u.pn * HALF + wc * 32 + 8 * fq;
; #pragma unroll
;     for (int ai = 0; ai < 2; ++ai)
; #pragma unroll
;       for (int m = 0; m < 4; ++m) {
;         const float r = rt[ai * HALF + wr * 64 + m * 16 + fr];
;         float a[8];
; #pragma unroll
;         for (int n = 0; n < 2; ++n)
; #pragma unroll
;           for (int j = 0; j < 4; ++j) { const float u1 = acc[ai][0][m][n][j] * r, u3 = acc[ai][1][m][n][j] * r; a[4 * n + j] = u1 * u3 * __builtin_amdgcn_rcpf(1.f + __builtin_amdgcn_exp2f(-LOG2E * u1)); }
;         u32x4 w; w.x = pack2(a[0], a[1]); w.y = pack2(a[2], a[3]); w.z = pack2(a[4], a[5]); w.w = pack2(a[6], a[7]);
;         *(u32x4*)(O + (size_t)(row0 + ai * HALF + m * 16) * DFF + col0) = w; }
;   }
	v_pk_mul_f32 v[56:57], v[54:55], v[56:57]
	v_mul_f32_e32 v54, 0xbfb8aa3b, v55
	v_exp_f32_e32 v60, v60
	v_exp_f32_e32 v54, v54
	v_pk_mul_f32 v[64:65], v[64:65], v[68:69]
	v_add_f32_e32 v60, 1.0, v60
	v_add_f32_e32 v54, 1.0, v54
	v_rcp_f32_e32 v60, v60
	v_rcp_f32_e32 v61, v54
	v_cvt_pk_bf16_f32 v54, v62, v63
	v_cvt_pk_bf16_f32 v55, v64, v65
	v_pk_mul_f32 v[60:61], v[56:57], v[60:61]
	v_cvt_pk_bf16_f32 v56, v58, v59
	v_mad_i64_i32 v[58:59], s[8:9], v74, s43, v[118:119]
	v_cvt_pk_bf16_f32 v57, v60, v61
	v_lshl_add_u64 v[58:59], v[58:59], 0, v[120:121]
	global_store_dwordx4 v[58:59], v[54:57], off
	s_nop 1
	v_mov_b32_e32 v54, v169
	v_pk_mul_f32 v[46:47], v[46:47], v[54:55] op_sel_hi:[1,0]
	s_nop 0
	v_mul_f32_e32 v55, 0xbfb8aa3b, v46
	v_exp_f32_e32 v55, v55
	s_nop 0
	v_add_f32_e32 v55, 1.0, v55
	v_pk_mul_f32 v[42:43], v[42:43], v[54:55] op_sel_hi:[1,0]
	v_pk_mul_f32 v[44:45], v[44:45], v[54:55] op_sel_hi:[1,0]
	v_pk_mul_f32 v[42:43], v[46:47], v[42:43]
	v_mul_f32_e32 v46, 0xbfb8aa3b, v47
	v_exp_f32_e32 v46, v46
	v_pk_mul_f32 v[38:39], v[38:39], v[54:55] op_sel_hi:[1,0]
	v_pk_mul_f32 v[34:35], v[34:35], v[54:55] op_sel_hi:[1,0]
	v_pk_mul_f32 v[36:37], v[36:37], v[54:55] op_sel_hi:[1,0]
	v_add_f32_e32 v46, 1.0, v46
	v_rcp_f32_e32 v57, v46
	v_pk_mul_f32 v[46:47], v[48:49], v[54:55] op_sel_hi:[1,0]
	v_pk_mul_f32 v[34:35], v[38:39], v[34:35]
	v_mul_f32_e32 v48, 0xbfb8aa3b, v46
	v_pk_mul_f32 v[44:45], v[46:47], v[44:45]
	v_mul_f32_e32 v46, 0xbfb8aa3b, v47
	v_exp_f32_e32 v46, v46
	v_exp_f32_e32 v48, v48
	v_rcp_f32_e32 v56, v55
	v_add_f32_e32 v46, 1.0, v46
	v_rcp_f32_e32 v49, v46
	v_mul_f32_e32 v46, 0xbfb8aa3b, v38
	v_mul_f32_e32 v38, 0xbfb8aa3b, v39
	v_exp_f32_e32 v46, v46
	v_exp_f32_e32 v38, v38
	v_add_f32_e32 v48, 1.0, v48
	v_rcp_f32_e32 v48, v48
	v_add_f32_e32 v46, 1.0, v46
	v_add_f32_e32 v38, 1.0, v38
	v_rcp_f32_e32 v46, v46
	v_rcp_f32_e32 v47, v38
	v_pk_mul_f32 v[42:43], v[42:43], v[56:57]
	v_pk_mul_f32 v[44:45], v[44:45], v[48:49]
	v_pk_mul_f32 v[38:39], v[34:35], v[46:47]
	v_pk_mul_f32 v[34:35], v[40:41], v[54:55] op_sel_hi:[1,0]
	s_nop 0
	v_mul_f32_e32 v40, 0xbfb8aa3b, v34
	v_pk_mul_f32 v[36:37], v[34:35], v[36:37]
	v_mul_f32_e32 v34, 0xbfb8aa3b, v35
	v_exp_f32_e32 v40, v40
	v_exp_f32_e32 v34, v34
	v_cvt_pk_bf16_f32 v35, v44, v45
	v_add_f32_e32 v40, 1.0, v40
	v_add_f32_e32 v34, 1.0, v34
	v_rcp_f32_e32 v40, v40
	v_rcp_f32_e32 v41, v34
	v_cvt_pk_bf16_f32 v34, v42, v43
	v_pk_mul_f32 v[40:41], v[36:37], v[40:41]
	v_cvt_pk_bf16_f32 v36, v38, v39
	v_add_u32_e32 v38, 0x90, v158
	v_mad_i64_i32 v[38:39], s[8:9], v38, s43, v[118:119]
	v_cvt_pk_bf16_f32 v37, v40, v41
	v_lshl_add_u64 v[38:39], v[38:39], 0, v[120:121]
	global_store_dwordx4 v[38:39], v[34:37], off
	s_waitcnt lgkmcnt(0)
	v_pk_mul_f32 v[30:31], v[30:31], v[170:171] op_sel_hi:[1,0]
	v_pk_mul_f32 v[26:27], v[26:27], v[170:171] op_sel_hi:[1,0]
	v_mul_f32_e32 v36, 0xbfb8aa3b, v30
	v_pk_mul_f32 v[26:27], v[30:31], v[26:27]
	v_mul_f32_e32 v30, 0xbfb8aa3b, v31
	v_exp_f32_e32 v30, v30
	v_pk_mul_f32 v[28:29], v[28:29], v[170:171] op_sel_hi:[1,0]
	v_pk_mul_f32 v[22:23], v[22:23], v[170:171] op_sel_hi:[1,0]
	v_pk_mul_f32 v[18:19], v[18:19], v[170:171] op_sel_hi:[1,0]
	v_add_f32_e32 v30, 1.0, v30
	v_rcp_f32_e32 v37, v30
	v_pk_mul_f32 v[30:31], v[32:33], v[170:171] op_sel_hi:[1,0]
	v_pk_mul_f32 v[18:19], v[22:23], v[18:19]
	v_mul_f32_e32 v32, 0xbfb8aa3b, v30
	v_pk_mul_f32 v[28:29], v[30:31], v[28:29]
	v_mul_f32_e32 v30, 0xbfb8aa3b, v31
	v_exp_f32_e32 v30, v30
	v_pk_mul_f32 v[20:21], v[20:21], v[170:171] op_sel_hi:[1,0]
	v_exp_f32_e32 v36, v36
	v_exp_f32_e32 v32, v32
	v_add_f32_e32 v30, 1.0, v30
	v_rcp_f32_e32 v33, v30
	v_mul_f32_e32 v30, 0xbfb8aa3b, v22
	v_mul_f32_e32 v22, 0xbfb8aa3b, v23
	v_exp_f32_e32 v30, v30
	v_exp_f32_e32 v22, v22
	v_add_f32_e32 v36, 1.0, v36
	v_add_f32_e32 v32, 1.0, v32
	v_add_f32_e32 v30, 1.0, v30
	v_add_f32_e32 v22, 1.0, v22
	v_rcp_f32_e32 v30, v30
	v_rcp_f32_e32 v31, v22
	v_rcp_f32_e32 v36, v36
	v_rcp_f32_e32 v32, v32
	v_pk_mul_f32 v[22:23], v[18:19], v[30:31]
	v_pk_mul_f32 v[18:19], v[24:25], v[170:171] op_sel_hi:[1,0]
	v_pk_mul_f32 v[26:27], v[26:27], v[36:37]
	v_mul_f32_e32 v24, 0xbfb8aa3b, v18
	v_pk_mul_f32 v[20:21], v[18:19], v[20:21]
	v_mul_f32_e32 v18, 0xbfb8aa3b, v19
	v_exp_f32_e32 v24, v24
	v_exp_f32_e32 v18, v18
	v_pk_mul_f32 v[28:29], v[28:29], v[32:33]
	v_add_f32_e32 v24, 1.0, v24
	v_add_f32_e32 v18, 1.0, v18
	v_rcp_f32_e32 v24, v24
	v_rcp_f32_e32 v25, v18
	v_cvt_pk_bf16_f32 v18, v26, v27
	v_cvt_pk_bf16_f32 v19, v28, v29
	v_pk_mul_f32 v[24:25], v[20:21], v[24:25]
	v_cvt_pk_bf16_f32 v20, v22, v23
	v_add_u32_e32 v22, 0xa0, v158
	v_mad_i64_i32 v[22:23], s[8:9], v22, s43, v[118:119]
	v_cvt_pk_bf16_f32 v21, v24, v25
	v_lshl_add_u64 v[22:23], v[22:23], 0, v[120:121]
	global_store_dwordx4 v[22:23], v[18:21], off
	s_nop 1
	v_mov_b32_e32 v18, v171
	v_pk_mul_f32 v[14:15], v[14:15], v[18:19] op_sel_hi:[1,0]
	s_nop 0
	v_mul_f32_e32 v19, 0xbfb8aa3b, v14
	v_exp_f32_e32 v19, v19
	s_nop 0
	v_add_f32_e32 v19, 1.0, v19
	v_pk_mul_f32 v[10:11], v[10:11], v[18:19] op_sel_hi:[1,0]
	v_pk_mul_f32 v[12:13], v[12:13], v[18:19] op_sel_hi:[1,0]
	v_pk_mul_f32 v[10:11], v[14:15], v[10:11]
	v_mul_f32_e32 v14, 0xbfb8aa3b, v15
	v_exp_f32_e32 v14, v14
	v_pk_mul_f32 v[6:7], v[6:7], v[18:19] op_sel_hi:[1,0]
	v_pk_mul_f32 v[2:3], v[2:3], v[18:19] op_sel_hi:[1,0]
	v_pk_mul_f32 v[4:5], v[4:5], v[18:19] op_sel_hi:[1,0]
	v_add_f32_e32 v14, 1.0, v14
	v_rcp_f32_e32 v21, v14
	v_pk_mul_f32 v[14:15], v[16:17], v[18:19] op_sel_hi:[1,0]
	v_pk_mul_f32 v[2:3], v[6:7], v[2:3]
	v_mul_f32_e32 v16, 0xbfb8aa3b, v14
	v_pk_mul_f32 v[12:13], v[14:15], v[12:13]
	v_mul_f32_e32 v14, 0xbfb8aa3b, v15
	v_exp_f32_e32 v14, v14
	v_exp_f32_e32 v16, v16
	v_rcp_f32_e32 v20, v19
	v_add_f32_e32 v14, 1.0, v14
	v_rcp_f32_e32 v17, v14
	v_mul_f32_e32 v14, 0xbfb8aa3b, v6
	v_mul_f32_e32 v6, 0xbfb8aa3b, v7
	v_exp_f32_e32 v14, v14
	v_exp_f32_e32 v6, v6
	v_add_f32_e32 v16, 1.0, v16
	v_rcp_f32_e32 v16, v16
	v_add_f32_e32 v14, 1.0, v14
	v_add_f32_e32 v6, 1.0, v6
	v_rcp_f32_e32 v14, v14
	v_rcp_f32_e32 v15, v6
	v_pk_mul_f32 v[10:11], v[10:11], v[20:21]
	v_pk_mul_f32 v[12:13], v[12:13], v[16:17]
	v_pk_mul_f32 v[6:7], v[2:3], v[14:15]
	v_pk_mul_f32 v[2:3], v[8:9], v[18:19] op_sel_hi:[1,0]
	s_nop 0
	v_mul_f32_e32 v8, 0xbfb8aa3b, v2
	v_pk_mul_f32 v[4:5], v[2:3], v[4:5]
	v_mul_f32_e32 v2, 0xbfb8aa3b, v3
	v_exp_f32_e32 v8, v8
	v_exp_f32_e32 v2, v2
	v_cvt_pk_bf16_f32 v3, v12, v13
	v_add_f32_e32 v8, 1.0, v8
	v_add_f32_e32 v2, 1.0, v2
	v_rcp_f32_e32 v8, v8
	v_rcp_f32_e32 v9, v2
	v_cvt_pk_bf16_f32 v2, v10, v11
	v_pk_mul_f32 v[8:9], v[4:5], v[8:9]
	v_cvt_pk_bf16_f32 v4, v6, v7
	v_add_u32_e32 v6, 0xb0, v158
	v_mad_i64_i32 v[6:7], s[8:9], v6, s43, v[118:119]
	v_cvt_pk_bf16_f32 v5, v8, v9
	v_lshl_add_u64 v[6:7], v[6:7], 0, v[120:121]
	global_store_dwordx4 v[6:7], v[2:5], off
	s_cbranch_vccnz .LBB0_597
; #define PG8_LAS __attribute__((address_space(3)))
;   DI void init(f32x4 (&acc)[2][2][4][2], const Unit&, int, int, int, int) const { acc_zero(acc); }
;   DI void init(f32x4 (&acc)[2][2][4][2], const Unit&, int, int, int, int) const { acc_zero(acc); }
; #define PG8_RTAB_LOAD(var, unit) do { if constexpr (Epi::NEEDS_R) { var = *(const uint4*)(E.ssq + (size_t)((unit).pm * BM + (tid >> 1)) * 16 + (tid & 1) * 8); } } while (0)
; #define PG8_RTAB_FIN(var, buf) do { if constexpr (Epi::NEEDS_R) { float ss_ = bflo(var.x) + bfhi(var.x) + bflo(var.y) + bfhi(var.y) + bflo(var.z) + bfhi(var.z) + bflo(var.w) + bfhi(var.w); ss_ += __shfl_xor(ss_, 1); \
;     if (!(tid & 1)) ((PG8_LAS float*)(lds + RT_OFF))[(buf) * 256 + (tid >> 1)] = rsqrtf(ss_ * (1.0f / DM) + EPS); } } while (0)
; template <class Epi>
; DI void gemm_phase(const bf16_t* __restrict__ gA, const bf16_t* __restrict__ gBt, int M, int N, int K, const Epi& E, char* lds_generic) {
;     ...
;     uint4 rtn_ = {0u, 0u, 0u, 0u};
;     if (has_next) PG8_RTAB_LOAD(rtn_, nxt);
;     E(acc, cur, wr, wc, fr, fq, (const PG8_LAS float*)(lds + RT_OFF) + (ui & 1) * 256);
;     if (!has_next) break;
;     PG8_RTAB_FIN(rtn_, (ui + 1) & 1);
;     E.init(acc, nxt, wr, wc, fr, fq);
	s_waitcnt vmcnt(8)
	v_lshlrev_b32_e32 v2, 16, v50
	v_and_b32_e32 v3, 0xffff0000, v50
	v_add_f32_e32 v2, v2, v3
	v_lshlrev_b32_e32 v3, 16, v51
	v_add_f32_e32 v2, v2, v3
	v_and_b32_e32 v3, 0xffff0000, v51
	v_add_f32_e32 v2, v2, v3
	v_lshlrev_b32_e32 v3, 16, v52
	v_add_f32_e32 v2, v2, v3
	v_and_b32_e32 v3, 0xffff0000, v52
	v_add_f32_e32 v2, v2, v3
	v_lshlrev_b32_e32 v3, 16, v53
	v_add_f32_e32 v2, v2, v3
	v_and_b32_e32 v3, 0xffff0000, v53
	v_add_f32_e32 v2, v2, v3
	s_nop 1
	v_mov_b32_dpp v3, v2 quad_perm:[1,0,3,2] row_mask:0xf bank_mask:0xf
	s_and_saveexec_b64 s[8:9], s[36:37]
	s_xor_b64 s[28:29], exec, s[8:9]
	s_cbranch_execz .LBB0_596
	s_waitcnt lgkmcnt(0)
	v_add_f32_e32 v2, v2, v3
	v_fmamk_f32 v2, v2, 0x3a800000, v234
	v_cmp_gt_f32_e32 vcc, s97, v2
	v_mul_f32_e32 v3, 0x4b800000, v2
	s_lshl_b32 s8, s18, 10
	v_cndmask_b32_e32 v2, v2, v3, vcc
	v_rsq_f32_e32 v2, v2
	s_and_b32 s8, s8, 0x400
	v_mul_f32_e32 v3, 0x45800000, v2
	v_cndmask_b32_e32 v2, v2, v3, vcc
	v_add_u32_e32 v3, s8, v152
	ds_write_b32 v3, v2
	s_branch .LBB0_596
